# prologue weight transposes: job lookup table kept in SGPRs instead of a per-item scalar-load search; SB wave min via DPP and lane swaps
# speedup vs baseline: 1.0192x; 1.0070x over previous
; #define LAS __attribute__((address_space(3)))
; __global__ void __launch_bounds__(512, 2) fwd_mega(Args args) {
;     ...
;     for (int rep_ = 0; rep_ < REP_P0; ++rep_) {
;         LAS float* scr = (LAS float*)(lds + wave * 16384);
;         for (int it = gw; it < args.nitems; it += NGW) {
;             int j = 0;
;             for (int q = 1; q < args.njobs; ++q) if (it >= args.jobs[q].item0) j = q;
;             transpose_item(args.jobs[j], scr, it - args.jobs[j].item0, lane);
.LBB0_7:
	s_or_b64 exec, exec, s[4:5]
	s_load_dwordx2 s[16:17], s[0:1], 0x768
	s_load_dwordx2 s[6:7], s[0:1], 0x770
	s_lshr_b32 s4, s3, 6
	s_lshl_b32 s3, s2, 3
	v_writelane_b32 v254, s3, 6
	s_add_i32 s3, s4, s3
	s_waitcnt lgkmcnt(0)
	s_lshl_b32 s42, s6, 3
	s_cmp_ge_i32 s3, s17
	s_cbranch_scc1 .LBB0_34
	s_lshl_b32 s4, s4, 14
	s_add_i32 s6, s4, 0
	s_cmp_gt_i32 s16, 1
	s_cselect_b64 s[4:5], -1, 0
	v_and_b32_e32 v3, 7, v204
	v_bfe_u32 v1, v204, 3, 3
	s_add_i32 s8, s16, -1
	v_lshlrev_b32_e32 v36, 2, v3
	v_lshl_add_u32 v4, v3, 4, s6
	v_lshlrev_b32_e32 v2, 3, v3
	v_mul_u32_u24_e32 v3, 0x420, v3
	v_lshlrev_b32_e32 v6, 2, v1
	s_cmp_lg_u32 s16, 2
	v_add3_u32 v45, s6, v3, v6
	s_cselect_b64 s[6:7], -1, 0
	s_and_b32 s14, s8, -2
	s_or_b32 s15, s8, 1
	s_cmp_lg_u32 s8, s14
	v_cndmask_b32_e64 v3, 0, 1, s[4:5]
	v_mov_b32_e32 v39, 0
	v_mul_u32_u24_e32 v5, 0x84, v1
	s_cselect_b64 s[18:19], -1, 0
	s_add_u32 s24, s0, 0x194
	v_cmp_ne_u32_e64 s[4:5], 1, v3
	v_cndmask_b32_e64 v3, 0, 1, s[6:7]
	v_or_b32_e32 v35, 8, v1
	v_or_b32_e32 v37, 16, v1
	v_or_b32_e32 v44, 24, v1
	s_addc_u32 s25, s1, 0
	v_lshlrev_b32_e32 v40, 2, v36
	v_mov_b32_e32 v41, v39
	v_add_u32_e32 v46, v4, v5
	v_lshlrev_b32_e32 v38, 1, v2
	v_cmp_ne_u32_e64 s[6:7], 1, v3
	s_load_dword s61, s[0:1], 0x1c4
	s_load_dword s62, s[0:1], 0x1f4
	s_load_dword s63, s[0:1], 0x224
	s_load_dword s64, s[0:1], 0x254
	s_load_dword s65, s[0:1], 0x284
	s_load_dword s66, s[0:1], 0x2b4
	s_load_dword s67, s[0:1], 0x2e4
	s_load_dword s68, s[0:1], 0x314
	s_load_dword s69, s[0:1], 0x344
	s_load_dword s70, s[0:1], 0x374
	s_load_dword s71, s[0:1], 0x3a4
	s_load_dword s72, s[0:1], 0x3d4
	s_load_dword s73, s[0:1], 0x404
	s_load_dword s74, s[0:1], 0x434
	s_load_dword s75, s[0:1], 0x464
	s_load_dword s76, s[0:1], 0x494
	s_load_dword s77, s[0:1], 0x4c4
	s_load_dword s78, s[0:1], 0x4f4
	s_load_dword s79, s[0:1], 0x524
	s_load_dword s80, s[0:1], 0x554
	s_load_dword s81, s[0:1], 0x584
	s_load_dword s82, s[0:1], 0x5b4
	s_load_dword s83, s[0:1], 0x5e4
	s_load_dword s84, s[0:1], 0x614
	s_load_dword s85, s[0:1], 0x644
	s_load_dword s86, s[0:1], 0x674
	s_load_dword s87, s[0:1], 0x6a4
	s_load_dword s88, s[0:1], 0x6d4
	s_load_dword s89, s[0:1], 0x704
	s_waitcnt lgkmcnt(0)
	s_branch .LBB0_10

; __global__ void __launch_bounds__(512, 2) fwd_mega(Args args) {
;     ...
;         for (int it = gw; it < args.nitems; it += NGW) {
;             int j = 0;
;             for (int q = 1; q < args.njobs; ++q) if (it >= args.jobs[q].item0) j = q;
;             transpose_item(args.jobs[j], scr, it - args.jobs[j].item0, lane);
.LBB0_10:
	s_mov_b32 s8, 0
	s_cmp_lt_i32 s3, s61
	s_cselect_b32 s8, s8, 1
	s_cmp_lt_i32 s3, s62
	s_cselect_b32 s8, s8, 2
	s_cmp_lt_i32 s3, s63
	s_cselect_b32 s8, s8, 3
	s_cmp_lt_i32 s3, s64
	s_cselect_b32 s8, s8, 4
	s_cmp_lt_i32 s3, s65
	s_cselect_b32 s8, s8, 5
	s_cmp_lt_i32 s3, s66
	s_cselect_b32 s8, s8, 6
	s_cmp_lt_i32 s3, s67
	s_cselect_b32 s8, s8, 7
	s_cmp_lt_i32 s3, s68
	s_cselect_b32 s8, s8, 8
	s_cmp_lt_i32 s3, s69
	s_cselect_b32 s8, s8, 9
	s_cmp_lt_i32 s3, s70
	s_cselect_b32 s8, s8, 10
	s_cmp_lt_i32 s3, s71
	s_cselect_b32 s8, s8, 11
	s_cmp_lt_i32 s3, s72
	s_cselect_b32 s8, s8, 12
	s_cmp_lt_i32 s3, s73
	s_cselect_b32 s8, s8, 13
	s_cmp_lt_i32 s3, s74
	s_cselect_b32 s8, s8, 14
	s_cmp_lt_i32 s3, s75
	s_cselect_b32 s8, s8, 15
	s_cmp_lt_i32 s3, s76
	s_cselect_b32 s8, s8, 16
	s_cmp_lt_i32 s3, s77
	s_cselect_b32 s8, s8, 17
	s_cmp_lt_i32 s3, s78
	s_cselect_b32 s8, s8, 18
	s_cmp_lt_i32 s3, s79
	s_cselect_b32 s8, s8, 19
	s_cmp_lt_i32 s3, s80
	s_cselect_b32 s8, s8, 20
	s_cmp_lt_i32 s3, s81
	s_cselect_b32 s8, s8, 21
	s_cmp_lt_i32 s3, s82
	s_cselect_b32 s8, s8, 22
	s_cmp_lt_i32 s3, s83
	s_cselect_b32 s8, s8, 23
	s_cmp_lt_i32 s3, s84
	s_cselect_b32 s8, s8, 24
	s_cmp_lt_i32 s3, s85
	s_cselect_b32 s8, s8, 25
	s_cmp_lt_i32 s3, s86
	s_cselect_b32 s8, s8, 26
	s_cmp_lt_i32 s3, s87
	s_cselect_b32 s8, s8, 27
	s_cmp_lt_i32 s3, s88
	s_cselect_b32 s8, s8, 28
	s_cmp_lt_i32 s3, s89
	s_cselect_b32 s8, s8, 29

; DEV float shx(float v, int m, int lane) { return __builtin_bit_cast(float, __builtin_amdgcn_ds_bpermute((lane ^ m) << 2, __builtin_bit_cast(int, v))); }
; DEV float wave_min(float v, int lane) {
; #pragma unroll
;     for (int o = 1; o < 64; o <<= 1) v = fminf(v, shx(v, o, lane));
;     return v;
; }
; DEV void sb_pass(LAS unsigned char* lds, int tid, int r, int h, int w, const bf16* Kp, size_t kpitch, const bf16* VTp, size_t vpitch, int t_hi, const bf16x8 (&qf)[4], int hi_lim, f32x16 (&o)[2]) {
;     ...
;         const float rmin = wave_min(Rr, lane);
;         if ((tid & 63) == 0) flags[par * 8 + w] = (rmin > 60.f) ? 1u : 0u;
.LBB0_184:
	s_nop 1
	v_min_f32_dpp v32, v103, v103 quad_perm:[1,0,3,2] row_mask:0xf bank_mask:0xf bound_ctrl:1
	s_nop 1
	v_min_f32_dpp v32, v32, v32 quad_perm:[2,3,0,1] row_mask:0xf bank_mask:0xf bound_ctrl:1
	s_nop 1
	v_min_f32_dpp v32, v32, v32 row_half_mirror row_mask:0xf bank_mask:0xf bound_ctrl:1
	s_nop 1
	v_min_f32_dpp v32, v32, v32 row_mirror row_mask:0xf bank_mask:0xf bound_ctrl:1
	v_mov_b32_e32 v33, v32
	s_nop 1
	v_permlane16_swap_b32_e32 v32, v33
	v_min_f32_e32 v32, v32, v33
	v_mov_b32_e32 v33, v32
	s_nop 1
	v_permlane32_swap_b32_e32 v32, v33
	v_min_f32_e32 v32, v32, v33
	s_and_saveexec_b64 s[6:7], s[4:5]
	s_cbranch_execz .LBB0_186
	v_cmp_lt_f32_e32 vcc, s40, v32
	v_lshl_add_u32 v33, s35, 5, v133
	s_nop 0
	v_cndmask_b32_e64 v32, 0, 1, vcc
	ds_write_b32 v33, v32
